# E34: E27 + non-temporal hint on the write-once final-norm output stores
# baseline (speedup 1.0000x reference)
; __device__ __forceinline__ float wave_sum(float v) {
; #pragma unroll
;     for (int o = 1; o < 64; o <<= 1) v += __shfl_xor(v, o);
;     return v;
; }
; __global__ void __launch_bounds__(NWAVES * 64, 2) mk_fwd(Args args) {
;     ...
;         for (int m = gw; m < SEQ; m += NGW) {
;             const f32x4* xr = (const f32x4*)(XR + (size_t)m * DMODEL) + lane;
;             f32x4 v[8]; float s = 0.f;
; #pragma unroll
;             for (int j = 0; j < 8; ++j) { v[j] = xr[64 * j]; s += (v[j][0] * v[j][0] + v[j][1] * v[j][1]) + (v[j][2] * v[j][2] + v[j][3] * v[j][3]); }
;             const float rstd = __builtin_amdgcn_rsqf(wave_sum(s) * (1.f / DMODEL) + EPS);
;             f32x4* o = (f32x4*)(out_p + (size_t)m * DMODEL) + lane;
; #pragma unroll
;             for (int j = 0; j < 8; ++j) { const f32x4 g = *((const f32x4*)final_norm_w + lane + 64 * j); o[64 * j] = v[j] * rstd * g; }
;         }
.Lfn_nopf:
	v_mul_f32_e32 v81, v21, v21
	v_pk_mul_f32 v[58:59], v[26:27], v[26:27]
	v_pk_mul_f32 v[60:61], v[24:25], v[24:25]
	v_mul_f32_e32 v62, v29, v29
	v_mul_f32_e32 v64, v31, v31
	v_mov_b32_e32 v68, v33
	v_mov_b32_e32 v69, v37
	v_mov_b32_e32 v72, v35
	v_mov_b32_e32 v73, v39
	v_mul_f32_e32 v88, v50, v50
	v_mul_f32_e32 v89, v51, v51
	v_mov_b32_e32 v66, v32
	v_mov_b32_e32 v67, v36
	v_mov_b32_e32 v70, v34
	v_mov_b32_e32 v71, v38
	v_pk_mul_f32 v[74:75], v[42:43], v[42:43]
	v_pk_mul_f32 v[76:77], v[40:41], v[40:41]
	v_pk_mov_b32 v[82:83], v[60:61], v[58:59] op_sel:[1,0]
	v_mov_b32_e32 v61, v59
	v_pk_fma_f32 v[58:59], v[28:29], v[28:29], v[62:63] op_sel_hi:[1,1,0]
	v_pk_fma_f32 v[62:63], v[30:31], v[30:31], v[64:65] op_sel_hi:[1,1,0]
	v_pk_mul_f32 v[64:65], v[68:69], v[68:69]
	v_pk_mul_f32 v[68:69], v[72:73], v[72:73]
	v_pk_mov_b32 v[72:73], v[76:77], v[74:75] op_sel:[1,0]
	v_mov_b32_e32 v77, v75
	v_mov_b32_e32 v59, v88
	v_mov_b32_e32 v63, v89
	v_pk_fma_f32 v[64:65], v[66:67], v[66:67], v[64:65]
	v_pk_fma_f32 v[66:67], v[70:71], v[70:71], v[68:69]
	v_mul_f32_e32 v78, v45, v45
	v_mul_f32_e32 v80, v47, v47
	v_pk_add_f32 v[68:69], v[72:73], v[76:77]
	v_pk_add_f32 v[58:59], v[58:59], v[62:63]
	v_pk_add_f32 v[62:63], v[64:65], v[66:67]
	v_mul_f32_e32 v19, v20, v20
	v_mul_f32_e32 v84, v22, v22
	v_mul_f32_e32 v85, v23, v23
	v_pk_fma_f32 v[74:75], v[44:45], v[44:45], v[78:79] op_sel_hi:[1,1,0]
	v_pk_fma_f32 v[78:79], v[46:47], v[46:47], v[80:81] op_sel_hi:[1,1,0]
	v_pk_add_f32 v[64:65], v[68:69], v[68:69] op_sel:[0,1] op_sel_hi:[1,0]
	v_pk_add_f32 v[62:63], v[62:63], v[62:63] op_sel:[0,1] op_sel_hi:[1,0]
	v_mov_b32_e32 v75, v84
	v_mov_b32_e32 v79, v85
	v_mov_b32_e32 v65, v81
	v_mov_b32_e32 v63, v19
	v_pk_add_f32 v[66:67], v[74:75], v[78:79]
	v_pk_add_f32 v[62:63], v[62:63], v[64:65]
	v_pk_add_f32 v[60:61], v[82:83], v[60:61]
	v_pk_add_f32 v[62:63], v[62:63], v[66:67]
	v_mul_f32_e32 v86, v48, v48
	v_mul_f32_e32 v87, v49, v49
	v_pk_add_f32 v[60:61], v[60:61], v[60:61] op_sel:[0,1] op_sel_hi:[1,0]
	v_pk_add_f32 v[62:63], v[62:63], v[62:63] op_sel:[0,1] op_sel_hi:[1,0]
	v_mov_b32_e32 v61, v87
	v_mov_b32_e32 v63, v86
	v_pk_add_f32 v[60:61], v[62:63], v[60:61]
	s_nop 0
	v_pk_add_f32 v[58:59], v[60:61], v[58:59]
	s_nop 0
	v_add_f32_e32 v19, v58, v59
	ds_bpermute_b32 v58, v12, v19
	s_waitcnt lgkmcnt(0)
	v_add_f32_e32 v19, v19, v58
	ds_bpermute_b32 v58, v13, v19
	s_waitcnt lgkmcnt(0)
	v_add_f32_e32 v19, v19, v58
	ds_bpermute_b32 v58, v14, v19
	s_waitcnt lgkmcnt(0)
	v_add_f32_e32 v19, v19, v58
	ds_bpermute_b32 v58, v15, v19
	s_waitcnt lgkmcnt(0)
	v_add_f32_e32 v19, v19, v58
	ds_bpermute_b32 v58, v16, v19
	s_waitcnt lgkmcnt(0)
	v_add_f32_e32 v19, v19, v58
	ds_bpermute_b32 v58, v17, v19
	s_waitcnt lgkmcnt(0)
	v_add_f32_e32 v19, v19, v58
	v_fmamk_f32 v19, v19, 0x3a000000, v18
	v_rsq_f32_e32 v58, v19
	s_nop 0
	v_pk_mul_f32 v[32:33], v[58:59], v[32:33] op_sel_hi:[0,1]
	v_pk_mul_f32 v[34:35], v[58:59], v[34:35] op_sel_hi:[0,1]
	v_pk_mul_f32 v[34:35], v[102:103], v[34:35]
	v_pk_mul_f32 v[32:33], v[100:101], v[32:33]
	global_store_dwordx4 v[56:57], v[32:35], off nt
	v_pk_mul_f32 v[38:39], v[58:59], v[38:39] op_sel_hi:[0,1]
	v_pk_mul_f32 v[36:37], v[58:59], v[36:37] op_sel_hi:[0,1]
	v_pk_mul_f32 v[22:23], v[58:59], v[22:23] op_sel_hi:[0,1]
	v_pk_mul_f32 v[20:21], v[58:59], v[20:21] op_sel_hi:[0,1]
	v_pk_mul_f32 v[26:27], v[58:59], v[26:27] op_sel_hi:[0,1]
	v_pk_mul_f32 v[24:25], v[58:59], v[24:25] op_sel_hi:[0,1]
	v_pk_mul_f32 v[32:33], v[104:105], v[36:37]
	v_pk_mul_f32 v[34:35], v[106:107], v[38:39]
	global_store_dwordx4 v[56:57], v[32:35], off offset:1024 nt
	v_pk_mul_f32 v[36:37], v[58:59], v[42:43] op_sel_hi:[0,1]
	v_pk_mul_f32 v[38:39], v[58:59], v[40:41] op_sel_hi:[0,1]
	v_pk_mul_f32 v[32:33], v[108:109], v[38:39]
	v_pk_mul_f32 v[34:35], v[110:111], v[36:37]
	global_store_dwordx4 v[56:57], v[32:35], off offset:2048 nt
	v_pk_mul_f32 v[36:37], v[58:59], v[46:47] op_sel_hi:[0,1]
	v_pk_mul_f32 v[38:39], v[58:59], v[44:45] op_sel_hi:[0,1]
	v_pk_mul_f32 v[32:33], v[112:113], v[38:39]
	v_pk_mul_f32 v[34:35], v[114:115], v[36:37]
	global_store_dwordx4 v[56:57], v[32:35], off offset:3072 nt
	v_add_co_u32_e32 v36, vcc, s8, v56
	v_pk_mul_f32 v[20:21], v[116:117], v[20:21]
	v_addc_co_u32_e32 v37, vcc, 0, v57, vcc
	v_pk_mul_f32 v[22:23], v[118:119], v[22:23]
	global_store_dwordx4 v[36:37], v[20:23], off nt
	s_nop 1
	v_pk_mul_f32 v[20:21], v[120:121], v[24:25]
	v_pk_mul_f32 v[22:23], v[122:123], v[26:27]
	global_store_dwordx4 v[36:37], v[20:23], off offset:1024 nt
	v_pk_mul_f32 v[24:25], v[58:59], v[30:31] op_sel_hi:[0,1]
	v_pk_mul_f32 v[26:27], v[58:59], v[28:29] op_sel_hi:[0,1]
	v_pk_mul_f32 v[20:21], v[124:125], v[26:27]
	v_pk_mul_f32 v[22:23], v[126:127], v[24:25]
	global_store_dwordx4 v[36:37], v[20:23], off offset:2048 nt
	v_pk_mul_f32 v[24:25], v[58:59], v[50:51] op_sel_hi:[0,1]
	v_pk_mul_f32 v[26:27], v[58:59], v[48:49] op_sel_hi:[0,1]
	v_pk_mul_f32 v[20:21], v[128:129], v[26:27]
	v_pk_mul_f32 v[22:23], v[130:131], v[24:25]
	global_store_dwordx4 v[36:37], v[20:23], off offset:3072 nt
	s_cbranch_scc1 .LBB0_885
